# in-proj q/k tiles: norm+rotary epilogue hand-rewritten (tables loaded once per unit, batched cross-lane sums, all 32 stores after the last load); on top of v14
# speedup vs baseline: 1.0015x; 1.0015x over previous
;     __device__ __forceinline__ void operator()(const f32x4 (&acc)[2][2][4][2], const Unit& u, int wr, int wc, int fr_, int fq_) const {
;     ...
;                     for (int bj = 0; bj < 2; ++bj)
; #pragma unroll
;                         for (int n = 0; n < 2; ++n) v[bj][n] = acc[ai][bj][m][n] * rstd;
;                     if (!isV) {
;                         float s = 0.f;
; #pragma unroll
;                         for (int bj = 0; bj < 2; ++bj)
; #pragma unroll
;                             for (int n = 0; n < 2; ++n) { const f32x4 x = v[bj][n]; s += (x[0] * x[0] + x[1] * x[1]) + (x[2] * x[2] + x[3] * x[3]); }
;                         s += __shfl_xor(s, 16); s += __shfl_xor(s, 32);
;                         const float rn = rsqrtf(s * (1.0f / 64.0f) + 1e-6f);
; #pragma unroll
;                         for (int bj = 0; bj < 2; ++bj)
; #pragma unroll
;                             for (int n = 0; n < 2; ++n) { const f32x4 w = *(const f32x4*)(nw + 32 * bj + 16 * n + 4 * fq); v[bj][n] = v[bj][n] * w * rn; }
;                         const int t = row & (S - 1), gr = t >> 6, gc = t & 63;
;                         const f32x4 c0 = *(const f32x4*)(ropeC + gr * 16 + 4 * fq), s0 = *(const f32x4*)(ropeS + gr * 16 + 4 * fq);
;                         const f32x4 c1 = *(const f32x4*)(ropeC + gc * 16 + 4 * fq), s1 = *(const f32x4*)(ropeS + gc * 16 + 4 * fq);
.LBB0_422:
	s_cmp_eq_u32 s40, 2
	s_cselect_b64 s[0:1], -1, 0
	s_and_b64 s[30:31], s[0:1], exec
	v_readlane_b32 s30, v255, 41
	v_readlane_b32 s31, v255, 42
	s_cselect_b32 s21, s14, s12
	s_cselect_b32 s23, s15, s13
	s_nop 1
	s_and_b64 s[36:37], s[0:1], s[30:31]
	v_readlane_b32 s30, v255, 52
	v_mov_b32_e32 v131, 0x3e38aa3b
	v_readlane_b32 s31, v255, 53
	s_nop 1
	s_add_u32 s30, s21, s30
	v_cndmask_b32_e64 v134, v131, 1.0, s[0:1]
	s_addc_u32 s31, s23, s31
	v_lshlrev_b32_e32 v136, 2, v170
	s_and_b64 vcc, exec, s[36:37]
	s_lshl_b32 s21, s40, 8
	v_readlane_b32 s40, v255, 39
	s_nop 1
	s_or_b32 s21, s21, s40
	s_and_b64 s[0:1], s[0:1], exec
	v_readlane_b32 s0, v253, 13
	v_readlane_b32 s1, v253, 14
	v_readlane_b32 s37, v253, 44
	s_cselect_b32 s36, 9, 10
	s_nop 1
	s_cselect_b32 s1, s37, s1
	v_readlane_b32 s37, v253, 43
	s_nop 1
	s_cselect_b32 s0, s37, s0
	s_cselect_b32 s48, s40, s21
	s_lshl_b32 s48, s48, 1
	v_lshl_add_u32 v137, v170, 1, s48
	s_cbranch_vccnz .Lqk_v
	global_load_dwordx4 v[150:153], v136, s[30:31]
	global_load_dwordx4 v[156:159], v136, s[30:31] offset:64
	global_load_dwordx2 v[160:161], v136, s[30:31] offset:128
	global_load_dwordx2 v[144:145], v136, s[30:31] offset:136
	global_load_dwordx2 v[204:205], v136, s[30:31] offset:192
	global_load_dwordx2 v[140:141], v136, s[30:31] offset:200
	v_and_b32_e32 v133, 0xffc0, v186
	v_and_b32_e32 v133, s47, v133
	v_add_u32_e32 v133, v133, v136
	global_load_dwordx4 v[242:245], v133, s[90:91]
	v_add_u32_e32 v133, 0x4000, v133
	global_load_dwordx4 v[246:249], v133, s[90:91]
	v_and_b32_e32 v133, 0xffc0, v178
	v_and_b32_e32 v133, s47, v133
	v_add_u32_e32 v133, v133, v136
	global_load_dwordx4 v[212:215], v133, s[90:91]
	v_add_u32_e32 v133, 0x4000, v133
	global_load_dwordx2 v[250:251], v133, s[90:91]
	global_load_dwordx2 v[216:217], v133, s[90:91] offset:8
	v_lshlrev_b32_e32 v133, 6, v186
	v_and_b32_e32 v133, 0xfc0, v133
	v_add_u32_e32 v133, v133, v136
	global_load_dwordx4 v[226:229], v133, s[90:91]
	v_add_u32_e32 v133, 0x4000, v133
	global_load_dwordx4 v[230:233], v133, s[90:91]
	v_lshlrev_b32_e32 v133, 6, v184
	v_and_b32_e32 v133, 0xfc0, v133
	v_add_u32_e32 v133, v133, v136
	global_load_dwordx4 v[234:237], v133, s[90:91]
	v_add_u32_e32 v133, 0x4000, v133
	global_load_dwordx4 v[238:241], v133, s[90:91]
	v_pk_mul_f32 v[196:197], v[118:119], v[118:119]
	v_pk_fma_f32 v[196:197], v[120:121], v[120:121], v[196:197]
	v_pk_fma_f32 v[196:197], v[114:115], v[114:115], v[196:197]
	v_pk_fma_f32 v[196:197], v[116:117], v[116:117], v[196:197]
	v_pk_fma_f32 v[196:197], v[126:127], v[126:127], v[196:197]
	v_pk_fma_f32 v[196:197], v[128:129], v[128:129], v[196:197]
	v_pk_fma_f32 v[196:197], v[122:123], v[122:123], v[196:197]
	v_pk_fma_f32 v[196:197], v[124:125], v[124:125], v[196:197]
	v_add_f32_e32 v188, v196, v197
	v_pk_mul_f32 v[196:197], v[106:107], v[106:107]
	v_pk_fma_f32 v[196:197], v[108:109], v[108:109], v[196:197]
	v_pk_fma_f32 v[196:197], v[98:99], v[98:99], v[196:197]
	v_pk_fma_f32 v[196:197], v[100:101], v[100:101], v[196:197]
	v_pk_fma_f32 v[196:197], v[110:111], v[110:111], v[196:197]
	v_pk_fma_f32 v[196:197], v[112:113], v[112:113], v[196:197]
	v_pk_fma_f32 v[196:197], v[102:103], v[102:103], v[196:197]
	v_pk_fma_f32 v[196:197], v[104:105], v[104:105], v[196:197]
	v_add_f32_e32 v189, v196, v197
	v_pk_mul_f32 v[196:197], v[90:91], v[90:91]
	v_pk_fma_f32 v[196:197], v[92:93], v[92:93], v[196:197]
	v_pk_fma_f32 v[196:197], v[82:83], v[82:83], v[196:197]
	v_pk_fma_f32 v[196:197], v[84:85], v[84:85], v[196:197]
	v_pk_fma_f32 v[196:197], v[94:95], v[94:95], v[196:197]
	v_pk_fma_f32 v[196:197], v[96:97], v[96:97], v[196:197]
	v_pk_fma_f32 v[196:197], v[86:87], v[86:87], v[196:197]
	v_pk_fma_f32 v[196:197], v[88:89], v[88:89], v[196:197]
	v_add_f32_e32 v190, v196, v197
	v_pk_mul_f32 v[196:197], v[74:75], v[74:75]
	v_pk_fma_f32 v[196:197], v[76:77], v[76:77], v[196:197]
	v_pk_fma_f32 v[196:197], v[66:67], v[66:67], v[196:197]
	v_pk_fma_f32 v[196:197], v[68:69], v[68:69], v[196:197]
	v_pk_fma_f32 v[196:197], v[78:79], v[78:79], v[196:197]
	v_pk_fma_f32 v[196:197], v[80:81], v[80:81], v[196:197]
	v_pk_fma_f32 v[196:197], v[70:71], v[70:71], v[196:197]
	v_pk_fma_f32 v[196:197], v[72:73], v[72:73], v[196:197]
	v_add_f32_e32 v191, v196, v197
	v_pk_mul_f32 v[196:197], v[58:59], v[58:59]
	v_pk_fma_f32 v[196:197], v[60:61], v[60:61], v[196:197]
	v_pk_fma_f32 v[196:197], v[50:51], v[50:51], v[196:197]
	v_pk_fma_f32 v[196:197], v[52:53], v[52:53], v[196:197]
	v_pk_fma_f32 v[196:197], v[62:63], v[62:63], v[196:197]
	v_pk_fma_f32 v[196:197], v[64:65], v[64:65], v[196:197]
	v_pk_fma_f32 v[196:197], v[54:55], v[54:55], v[196:197]
	v_pk_fma_f32 v[196:197], v[56:57], v[56:57], v[196:197]
	v_add_f32_e32 v192, v196, v197
	v_pk_mul_f32 v[196:197], v[42:43], v[42:43]
	v_pk_fma_f32 v[196:197], v[44:45], v[44:45], v[196:197]
	v_pk_fma_f32 v[196:197], v[34:35], v[34:35], v[196:197]
	v_pk_fma_f32 v[196:197], v[36:37], v[36:37], v[196:197]
	v_pk_fma_f32 v[196:197], v[46:47], v[46:47], v[196:197]
	v_pk_fma_f32 v[196:197], v[48:49], v[48:49], v[196:197]
	v_pk_fma_f32 v[196:197], v[38:39], v[38:39], v[196:197]
	v_pk_fma_f32 v[196:197], v[40:41], v[40:41], v[196:197]
	v_add_f32_e32 v193, v196, v197
	v_pk_mul_f32 v[196:197], v[26:27], v[26:27]
	v_pk_fma_f32 v[196:197], v[28:29], v[28:29], v[196:197]
	v_pk_fma_f32 v[196:197], v[18:19], v[18:19], v[196:197]
	v_pk_fma_f32 v[196:197], v[20:21], v[20:21], v[196:197]
	v_pk_fma_f32 v[196:197], v[30:31], v[30:31], v[196:197]
	v_pk_fma_f32 v[196:197], v[32:33], v[32:33], v[196:197]
	v_pk_fma_f32 v[196:197], v[22:23], v[22:23], v[196:197]
	v_pk_fma_f32 v[196:197], v[24:25], v[24:25], v[196:197]
	v_add_f32_e32 v194, v196, v197
	v_pk_mul_f32 v[196:197], v[10:11], v[10:11]
	v_pk_fma_f32 v[196:197], v[12:13], v[12:13], v[196:197]
	v_pk_fma_f32 v[196:197], v[2:3], v[2:3], v[196:197]
	v_pk_fma_f32 v[196:197], v[4:5], v[4:5], v[196:197]
	v_pk_fma_f32 v[196:197], v[14:15], v[14:15], v[196:197]
	v_pk_fma_f32 v[196:197], v[16:17], v[16:17], v[196:197]
	v_pk_fma_f32 v[196:197], v[6:7], v[6:7], v[196:197]
	v_pk_fma_f32 v[196:197], v[8:9], v[8:9], v[196:197]
	v_add_f32_e32 v195, v196, v197
	ds_bpermute_b32 v196, v210, v188
	ds_bpermute_b32 v197, v210, v189
	ds_bpermute_b32 v131, v210, v190
	ds_bpermute_b32 v135, v210, v191
	ds_bpermute_b32 v208, v210, v192
	ds_bpermute_b32 v209, v210, v193
	ds_bpermute_b32 v139, v210, v194
	ds_bpermute_b32 v133, v210, v195
	s_waitcnt lgkmcnt(0)
; __device__ __forceinline__ unsigned cvt_pk_bf16(float lo, float hi) { unsigned r; asm volatile("v_cvt_pk_bf16_f32 %0, %1, %2" : "=v"(r) : "v"(lo), "v"(hi)); return r; }
;     __device__ __forceinline__ void operator()(const f32x4 (&acc)[2][2][4][2], const Unit& u, int wr, int wc, int fr_, int fq_) const {
;     ...
;                     if (!isV) {
;                         float s = 0.f;
; #pragma unroll
;                         for (int bj = 0; bj < 2; ++bj)
; #pragma unroll
;                             for (int n = 0; n < 2; ++n) { const f32x4 x = v[bj][n]; s += (x[0] * x[0] + x[1] * x[1]) + (x[2] * x[2] + x[3] * x[3]); }
;                         s += __shfl_xor(s, 16); s += __shfl_xor(s, 32);
;                         const float rn = rsqrtf(s * (1.0f / 64.0f) + 1e-6f);
; #pragma unroll
;                         for (int bj = 0; bj < 2; ++bj)
; #pragma unroll
;                             for (int n = 0; n < 2; ++n) { const f32x4 w = *(const f32x4*)(nw + 32 * bj + 16 * n + 4 * fq); v[bj][n] = v[bj][n] * w * rn; }
;                         const int t = row & (S - 1), gr = t >> 6, gc = t & 63;
;                         const f32x4 c0 = *(const f32x4*)(ropeC + gr * 16 + 4 * fq), s0 = *(const f32x4*)(ropeS + gr * 16 + 4 * fq);
;                         const f32x4 c1 = *(const f32x4*)(ropeC + gc * 16 + 4 * fq), s1 = *(const f32x4*)(ropeS + gc * 16 + 4 * fq);
;                         { const f32x4 x1 = v[0][0], x2 = v[0][1]; v[0][0] = (x1 * c0 - x2 * s0) * osc; v[0][1] = (x2 * c0 + x1 * s0) * osc; }
;                         { const f32x4 x1 = v[1][0], x2 = v[1][1]; v[1][0] = (x1 * c1 - x2 * s1) * osc; v[1][1] = (x2 * c1 + x1 * s1) * osc; }
;                     }
;                     bf16_t* dst = (pn < 2) ? QA + (size_t)row * 512 + (4 * pn + wc) * 64 : KVA + (size_t)row * 256 + wc * 64;
; #pragma unroll
;                     for (int bj = 0; bj < 2; ++bj)
; #pragma unroll
;                         for (int n = 0; n < 2; ++n) { u32x2 w; w.x = cvt_pk_bf16(v[bj][n][0], v[bj][n][1]); w.y = cvt_pk_bf16(v[bj][n][2], v[bj][n][3]); *(u32x2*)(dst + 32 * bj + 16 * n + 4 * fq) = w; }
	v_add_f32_e32 v188, v188, v196
	v_add_f32_e32 v189, v189, v197
	v_add_f32_e32 v190, v190, v131
	v_add_f32_e32 v191, v191, v135
	v_add_f32_e32 v192, v192, v208
	v_add_f32_e32 v193, v193, v209
	v_add_f32_e32 v194, v194, v139
	v_add_f32_e32 v195, v195, v133
	ds_bpermute_b32 v196, v211, v188
	ds_bpermute_b32 v197, v211, v189
	ds_bpermute_b32 v131, v211, v190
	ds_bpermute_b32 v135, v211, v191
	ds_bpermute_b32 v208, v211, v192
	ds_bpermute_b32 v209, v211, v193
	ds_bpermute_b32 v139, v211, v194
	ds_bpermute_b32 v133, v211, v195
	s_waitcnt lgkmcnt(0)
	v_add_f32_e32 v188, v188, v196
	v_add_f32_e32 v189, v189, v197
	v_add_f32_e32 v190, v190, v131
	v_add_f32_e32 v191, v191, v135
	v_add_f32_e32 v192, v192, v208
	v_add_f32_e32 v193, v193, v209
	v_add_f32_e32 v194, v194, v139
	v_add_f32_e32 v195, v195, v133
	v_mul_f32_e32 v188, v188, v0
	v_mul_f32_e32 v189, v189, v154
	v_mul_f32_e32 v190, v190, v148
	v_mul_f32_e32 v191, v191, v146
	v_mul_f32_e32 v192, v192, v142
	v_mul_f32_e32 v193, v193, v138
	v_mul_f32_e32 v194, v194, v132
	v_mul_f32_e32 v195, v195, v130
	v_mul_f32_e32 v188, v188, v0
	v_mul_f32_e32 v189, v189, v154
	v_mul_f32_e32 v190, v190, v148
	v_mul_f32_e32 v191, v191, v146
	v_mul_f32_e32 v192, v192, v142
	v_mul_f32_e32 v193, v193, v138
	v_mul_f32_e32 v194, v194, v132
	v_mul_f32_e32 v195, v195, v130
	v_fmamk_f32 v188, v188, 0x3c800000, v252
	v_fmamk_f32 v189, v189, 0x3c800000, v252
	v_fmamk_f32 v190, v190, 0x3c800000, v252
	v_fmamk_f32 v191, v191, 0x3c800000, v252
	v_fmamk_f32 v192, v192, 0x3c800000, v252
	v_fmamk_f32 v193, v193, 0x3c800000, v252
	v_fmamk_f32 v194, v194, 0x3c800000, v252
	v_fmamk_f32 v195, v195, 0x3c800000, v252
	v_rsq_f32_e32 v188, v188
	v_rsq_f32_e32 v189, v189
	v_rsq_f32_e32 v190, v190
	v_rsq_f32_e32 v191, v191
	v_rsq_f32_e32 v192, v192
	v_rsq_f32_e32 v193, v193
	v_rsq_f32_e32 v194, v194
	v_rsq_f32_e32 v195, v195
	v_mul_f32_e32 v0, v0, v188
	v_mul_f32_e32 v154, v154, v189
	v_mul_f32_e32 v148, v148, v190
	v_mul_f32_e32 v146, v146, v191
	v_mul_f32_e32 v142, v142, v192
	v_mul_f32_e32 v138, v138, v193
	v_mul_f32_e32 v132, v132, v194
	v_mul_f32_e32 v130, v130, v195
	v_mul_f32_e32 v0, v0, v134
	v_mul_f32_e32 v154, v154, v134
	v_mul_f32_e32 v148, v148, v134
	v_mul_f32_e32 v146, v146, v134
	v_mul_f32_e32 v142, v142, v134
	v_mul_f32_e32 v138, v138, v134
	v_mul_f32_e32 v132, v132, v134
	v_mul_f32_e32 v130, v130, v134
	s_waitcnt vmcnt(2)
	v_pk_mul_f32 v[118:119], v[118:119], v[150:151]
	v_pk_mul_f32 v[120:121], v[120:121], v[152:153]
	v_pk_mul_f32 v[114:115], v[114:115], v[156:157]
	v_pk_mul_f32 v[116:117], v[116:117], v[158:159]
	v_pk_mul_f32 v[126:127], v[126:127], v[160:161]
	v_pk_mul_f32 v[128:129], v[128:129], v[144:145]
	v_pk_mul_f32 v[122:123], v[122:123], v[204:205]
	v_pk_mul_f32 v[124:125], v[124:125], v[140:141]
	v_pk_mul_f32 v[188:189], v[114:115], v[246:247]
	v_pk_mul_f32 v[192:193], v[118:119], v[246:247]
	v_pk_mul_f32 v[190:191], v[116:117], v[248:249]
	v_pk_mul_f32 v[194:195], v[120:121], v[248:249]
	v_pk_fma_f32 v[118:119], v[118:119], v[242:243], v[188:189] neg_lo:[0,0,1] neg_hi:[0,0,1]
	v_pk_fma_f32 v[114:115], v[114:115], v[242:243], v[192:193]
	v_pk_fma_f32 v[120:121], v[120:121], v[244:245], v[190:191] neg_lo:[0,0,1] neg_hi:[0,0,1]
	v_pk_fma_f32 v[116:117], v[116:117], v[244:245], v[194:195]
	v_pk_mul_f32 v[188:189], v[122:123], v[230:231]
	v_pk_mul_f32 v[192:193], v[126:127], v[230:231]
	v_pk_mul_f32 v[190:191], v[124:125], v[232:233]
	v_pk_mul_f32 v[194:195], v[128:129], v[232:233]
	v_pk_fma_f32 v[126:127], v[126:127], v[226:227], v[188:189] neg_lo:[0,0,1] neg_hi:[0,0,1]
	v_pk_fma_f32 v[122:123], v[122:123], v[226:227], v[192:193]
	v_pk_fma_f32 v[128:129], v[128:129], v[228:229], v[190:191] neg_lo:[0,0,1] neg_hi:[0,0,1]
	v_pk_fma_f32 v[124:125], v[124:125], v[228:229], v[194:195]
	v_pk_mul_f32 v[118:119], v[118:119], v[0:1] op_sel_hi:[1,0]
	v_pk_mul_f32 v[120:121], v[120:121], v[0:1] op_sel_hi:[1,0]
	v_pk_mul_f32 v[114:115], v[114:115], v[0:1] op_sel_hi:[1,0]
	v_pk_mul_f32 v[116:117], v[116:117], v[0:1] op_sel_hi:[1,0]
	v_pk_mul_f32 v[126:127], v[126:127], v[0:1] op_sel_hi:[1,0]
	v_pk_mul_f32 v[128:129], v[128:129], v[0:1] op_sel_hi:[1,0]
	v_pk_mul_f32 v[122:123], v[122:123], v[0:1] op_sel_hi:[1,0]
	v_pk_mul_f32 v[124:125], v[124:125], v[0:1] op_sel_hi:[1,0]
	v_cvt_pk_bf16_f32 v118, v118, v119
	v_cvt_pk_bf16_f32 v119, v120, v121
	v_cvt_pk_bf16_f32 v114, v114, v115
	v_cvt_pk_bf16_f32 v115, v116, v117
	v_cvt_pk_bf16_f32 v126, v126, v127
	v_cvt_pk_bf16_f32 v127, v128, v129
	v_cvt_pk_bf16_f32 v122, v122, v123
	v_cvt_pk_bf16_f32 v123, v124, v125
	v_pk_mul_f32 v[58:59], v[58:59], v[150:151]
	v_pk_mul_f32 v[60:61], v[60:61], v[152:153]
	v_pk_mul_f32 v[50:51], v[50:51], v[156:157]
	v_pk_mul_f32 v[52:53], v[52:53], v[158:159]
	v_pk_mul_f32 v[62:63], v[62:63], v[160:161]
	v_pk_mul_f32 v[64:65], v[64:65], v[144:145]
	v_pk_mul_f32 v[54:55], v[54:55], v[204:205]
	v_pk_mul_f32 v[56:57], v[56:57], v[140:141]
	v_pk_mul_f32 v[188:189], v[50:51], v[250:251]
	v_pk_mul_f32 v[192:193], v[58:59], v[250:251]
	v_pk_mul_f32 v[190:191], v[52:53], v[216:217]
	v_pk_mul_f32 v[194:195], v[60:61], v[216:217]
	v_pk_fma_f32 v[58:59], v[58:59], v[212:213], v[188:189] neg_lo:[0,0,1] neg_hi:[0,0,1]
	v_pk_fma_f32 v[50:51], v[50:51], v[212:213], v[192:193]
	v_pk_fma_f32 v[60:61], v[60:61], v[214:215], v[190:191] neg_lo:[0,0,1] neg_hi:[0,0,1]
	v_pk_fma_f32 v[52:53], v[52:53], v[214:215], v[194:195]
	v_pk_mul_f32 v[188:189], v[54:55], v[230:231]
	v_pk_mul_f32 v[192:193], v[62:63], v[230:231]
	v_pk_mul_f32 v[190:191], v[56:57], v[232:233]
	v_pk_mul_f32 v[194:195], v[64:65], v[232:233]
	v_pk_fma_f32 v[62:63], v[62:63], v[226:227], v[188:189] neg_lo:[0,0,1] neg_hi:[0,0,1]
	v_pk_fma_f32 v[54:55], v[54:55], v[226:227], v[192:193]
	v_pk_fma_f32 v[64:65], v[64:65], v[228:229], v[190:191] neg_lo:[0,0,1] neg_hi:[0,0,1]
	v_pk_fma_f32 v[56:57], v[56:57], v[228:229], v[194:195]
	v_pk_mul_f32 v[58:59], v[58:59], v[142:143] op_sel_hi:[1,0]
	v_pk_mul_f32 v[60:61], v[60:61], v[142:143] op_sel_hi:[1,0]
	v_pk_mul_f32 v[50:51], v[50:51], v[142:143] op_sel_hi:[1,0]
	v_pk_mul_f32 v[52:53], v[52:53], v[142:143] op_sel_hi:[1,0]
	v_pk_mul_f32 v[62:63], v[62:63], v[142:143] op_sel_hi:[1,0]
	v_pk_mul_f32 v[64:65], v[64:65], v[142:143] op_sel_hi:[1,0]
	v_pk_mul_f32 v[54:55], v[54:55], v[142:143] op_sel_hi:[1,0]
	v_pk_mul_f32 v[56:57], v[56:57], v[142:143] op_sel_hi:[1,0]
	v_cvt_pk_bf16_f32 v58, v58, v59
	v_cvt_pk_bf16_f32 v59, v60, v61
	v_cvt_pk_bf16_f32 v50, v50, v51
	v_cvt_pk_bf16_f32 v51, v52, v53
	v_cvt_pk_bf16_f32 v62, v62, v63
	v_cvt_pk_bf16_f32 v63, v64, v65
	v_cvt_pk_bf16_f32 v54, v54, v55
	v_cvt_pk_bf16_f32 v55, v56, v57
	v_lshlrev_b32_e32 v133, 6, v182
	v_and_b32_e32 v133, 0xfc0, v133
	v_add_u32_e32 v133, v133, v136
	global_load_dwordx4 v[226:229], v133, s[90:91]
	v_add_u32_e32 v133, 0x4000, v133
	global_load_dwordx4 v[230:233], v133, s[90:91]
	s_waitcnt vmcnt(2)
; __device__ __forceinline__ unsigned cvt_pk_bf16(float lo, float hi) { unsigned r; asm volatile("v_cvt_pk_bf16_f32 %0, %1, %2" : "=v"(r) : "v"(lo), "v"(hi)); return r; }
;     __device__ __forceinline__ void operator()(const f32x4 (&acc)[2][2][4][2], const Unit& u, int wr, int wc, int fr_, int fq_) const {
;     ...
; #pragma unroll
;                         for (int bj = 0; bj < 2; ++bj)
; #pragma unroll
;                             for (int n = 0; n < 2; ++n) { const f32x4 w = *(const f32x4*)(nw + 32 * bj + 16 * n + 4 * fq); v[bj][n] = v[bj][n] * w * rn; }
;                         const int t = row & (S - 1), gr = t >> 6, gc = t & 63;
;                         const f32x4 c0 = *(const f32x4*)(ropeC + gr * 16 + 4 * fq), s0 = *(const f32x4*)(ropeS + gr * 16 + 4 * fq);
;                         const f32x4 c1 = *(const f32x4*)(ropeC + gc * 16 + 4 * fq), s1 = *(const f32x4*)(ropeS + gc * 16 + 4 * fq);
;                         { const f32x4 x1 = v[0][0], x2 = v[0][1]; v[0][0] = (x1 * c0 - x2 * s0) * osc; v[0][1] = (x2 * c0 + x1 * s0) * osc; }
;                         { const f32x4 x1 = v[1][0], x2 = v[1][1]; v[1][0] = (x1 * c1 - x2 * s1) * osc; v[1][1] = (x2 * c1 + x1 * s1) * osc; }
;                     }
;                     bf16_t* dst = (pn < 2) ? QA + (size_t)row * 512 + (4 * pn + wc) * 64 : KVA + (size_t)row * 256 + wc * 64;
; #pragma unroll
;                     for (int bj = 0; bj < 2; ++bj)
; #pragma unroll
;                         for (int n = 0; n < 2; ++n) { u32x2 w; w.x = cvt_pk_bf16(v[bj][n][0], v[bj][n][1]); w.y = cvt_pk_bf16(v[bj][n][2], v[bj][n][3]); *(u32x2*)(dst + 32 * bj + 16 * n + 4 * fq) = w; }
	v_pk_mul_f32 v[106:107], v[106:107], v[150:151]
	v_pk_mul_f32 v[108:109], v[108:109], v[152:153]
	v_pk_mul_f32 v[98:99], v[98:99], v[156:157]
	v_pk_mul_f32 v[100:101], v[100:101], v[158:159]
	v_pk_mul_f32 v[110:111], v[110:111], v[160:161]
	v_pk_mul_f32 v[112:113], v[112:113], v[144:145]
	v_pk_mul_f32 v[102:103], v[102:103], v[204:205]
	v_pk_mul_f32 v[104:105], v[104:105], v[140:141]
	v_pk_mul_f32 v[188:189], v[98:99], v[246:247]
	v_pk_mul_f32 v[192:193], v[106:107], v[246:247]
	v_pk_mul_f32 v[190:191], v[100:101], v[248:249]
	v_pk_mul_f32 v[194:195], v[108:109], v[248:249]
	v_pk_fma_f32 v[106:107], v[106:107], v[242:243], v[188:189] neg_lo:[0,0,1] neg_hi:[0,0,1]
	v_pk_fma_f32 v[98:99], v[98:99], v[242:243], v[192:193]
	v_pk_fma_f32 v[108:109], v[108:109], v[244:245], v[190:191] neg_lo:[0,0,1] neg_hi:[0,0,1]
	v_pk_fma_f32 v[100:101], v[100:101], v[244:245], v[194:195]
	v_pk_mul_f32 v[188:189], v[102:103], v[238:239]
	v_pk_mul_f32 v[192:193], v[110:111], v[238:239]
	v_pk_mul_f32 v[190:191], v[104:105], v[240:241]
	v_pk_mul_f32 v[194:195], v[112:113], v[240:241]
	v_pk_fma_f32 v[110:111], v[110:111], v[234:235], v[188:189] neg_lo:[0,0,1] neg_hi:[0,0,1]
	v_pk_fma_f32 v[102:103], v[102:103], v[234:235], v[192:193]
	v_pk_fma_f32 v[112:113], v[112:113], v[236:237], v[190:191] neg_lo:[0,0,1] neg_hi:[0,0,1]
	v_pk_fma_f32 v[104:105], v[104:105], v[236:237], v[194:195]
	v_pk_mul_f32 v[106:107], v[106:107], v[154:155] op_sel_hi:[1,0]
	v_pk_mul_f32 v[108:109], v[108:109], v[154:155] op_sel_hi:[1,0]
	v_pk_mul_f32 v[98:99], v[98:99], v[154:155] op_sel_hi:[1,0]
	v_pk_mul_f32 v[100:101], v[100:101], v[154:155] op_sel_hi:[1,0]
	v_pk_mul_f32 v[110:111], v[110:111], v[154:155] op_sel_hi:[1,0]
	v_pk_mul_f32 v[112:113], v[112:113], v[154:155] op_sel_hi:[1,0]
	v_pk_mul_f32 v[102:103], v[102:103], v[154:155] op_sel_hi:[1,0]
	v_pk_mul_f32 v[104:105], v[104:105], v[154:155] op_sel_hi:[1,0]
	v_cvt_pk_bf16_f32 v106, v106, v107
	v_cvt_pk_bf16_f32 v107, v108, v109
	v_cvt_pk_bf16_f32 v98, v98, v99
	v_cvt_pk_bf16_f32 v99, v100, v101
	v_cvt_pk_bf16_f32 v110, v110, v111
	v_cvt_pk_bf16_f32 v111, v112, v113
	v_cvt_pk_bf16_f32 v102, v102, v103
	v_cvt_pk_bf16_f32 v103, v104, v105
	v_pk_mul_f32 v[42:43], v[42:43], v[150:151]
	v_pk_mul_f32 v[44:45], v[44:45], v[152:153]
	v_pk_mul_f32 v[34:35], v[34:35], v[156:157]
	v_pk_mul_f32 v[36:37], v[36:37], v[158:159]
	v_pk_mul_f32 v[46:47], v[46:47], v[160:161]
	v_pk_mul_f32 v[48:49], v[48:49], v[144:145]
	v_pk_mul_f32 v[38:39], v[38:39], v[204:205]
	v_pk_mul_f32 v[40:41], v[40:41], v[140:141]
	v_pk_mul_f32 v[188:189], v[34:35], v[250:251]
	v_pk_mul_f32 v[192:193], v[42:43], v[250:251]
	v_pk_mul_f32 v[190:191], v[36:37], v[216:217]
	v_pk_mul_f32 v[194:195], v[44:45], v[216:217]
	v_pk_fma_f32 v[42:43], v[42:43], v[212:213], v[188:189] neg_lo:[0,0,1] neg_hi:[0,0,1]
	v_pk_fma_f32 v[34:35], v[34:35], v[212:213], v[192:193]
	v_pk_fma_f32 v[44:45], v[44:45], v[214:215], v[190:191] neg_lo:[0,0,1] neg_hi:[0,0,1]
	v_pk_fma_f32 v[36:37], v[36:37], v[214:215], v[194:195]
	v_pk_mul_f32 v[188:189], v[38:39], v[238:239]
	v_pk_mul_f32 v[192:193], v[46:47], v[238:239]
	v_pk_mul_f32 v[190:191], v[40:41], v[240:241]
	v_pk_mul_f32 v[194:195], v[48:49], v[240:241]
	v_pk_fma_f32 v[46:47], v[46:47], v[234:235], v[188:189] neg_lo:[0,0,1] neg_hi:[0,0,1]
	v_pk_fma_f32 v[38:39], v[38:39], v[234:235], v[192:193]
	v_pk_fma_f32 v[48:49], v[48:49], v[236:237], v[190:191] neg_lo:[0,0,1] neg_hi:[0,0,1]
	v_pk_fma_f32 v[40:41], v[40:41], v[236:237], v[194:195]
	v_pk_mul_f32 v[42:43], v[42:43], v[138:139] op_sel_hi:[1,0]
	v_pk_mul_f32 v[44:45], v[44:45], v[138:139] op_sel_hi:[1,0]
	v_pk_mul_f32 v[34:35], v[34:35], v[138:139] op_sel_hi:[1,0]
	v_pk_mul_f32 v[36:37], v[36:37], v[138:139] op_sel_hi:[1,0]
	v_pk_mul_f32 v[46:47], v[46:47], v[138:139] op_sel_hi:[1,0]
	v_pk_mul_f32 v[48:49], v[48:49], v[138:139] op_sel_hi:[1,0]
	v_pk_mul_f32 v[38:39], v[38:39], v[138:139] op_sel_hi:[1,0]
	v_pk_mul_f32 v[40:41], v[40:41], v[138:139] op_sel_hi:[1,0]
	v_cvt_pk_bf16_f32 v42, v42, v43
	v_cvt_pk_bf16_f32 v43, v44, v45
	v_cvt_pk_bf16_f32 v34, v34, v35
	v_cvt_pk_bf16_f32 v35, v36, v37
	v_cvt_pk_bf16_f32 v46, v46, v47
	v_cvt_pk_bf16_f32 v47, v48, v49
	v_cvt_pk_bf16_f32 v38, v38, v39
	v_cvt_pk_bf16_f32 v39, v40, v41
	v_lshlrev_b32_e32 v133, 6, v180
	v_and_b32_e32 v133, 0xfc0, v133
	v_add_u32_e32 v133, v133, v136
	global_load_dwordx4 v[234:237], v133, s[90:91]
	v_add_u32_e32 v133, 0x4000, v133
	global_load_dwordx4 v[238:241], v133, s[90:91]
	s_waitcnt vmcnt(2)
; __device__ __forceinline__ unsigned cvt_pk_bf16(float lo, float hi) { unsigned r; asm volatile("v_cvt_pk_bf16_f32 %0, %1, %2" : "=v"(r) : "v"(lo), "v"(hi)); return r; }
;     __device__ __forceinline__ void operator()(const f32x4 (&acc)[2][2][4][2], const Unit& u, int wr, int wc, int fr_, int fq_) const {
;     ...
; #pragma unroll
;                         for (int bj = 0; bj < 2; ++bj)
; #pragma unroll
;                             for (int n = 0; n < 2; ++n) { const f32x4 w = *(const f32x4*)(nw + 32 * bj + 16 * n + 4 * fq); v[bj][n] = v[bj][n] * w * rn; }
;                         const int t = row & (S - 1), gr = t >> 6, gc = t & 63;
;                         const f32x4 c0 = *(const f32x4*)(ropeC + gr * 16 + 4 * fq), s0 = *(const f32x4*)(ropeS + gr * 16 + 4 * fq);
;                         const f32x4 c1 = *(const f32x4*)(ropeC + gc * 16 + 4 * fq), s1 = *(const f32x4*)(ropeS + gc * 16 + 4 * fq);
;                         { const f32x4 x1 = v[0][0], x2 = v[0][1]; v[0][0] = (x1 * c0 - x2 * s0) * osc; v[0][1] = (x2 * c0 + x1 * s0) * osc; }
;                         { const f32x4 x1 = v[1][0], x2 = v[1][1]; v[1][0] = (x1 * c1 - x2 * s1) * osc; v[1][1] = (x2 * c1 + x1 * s1) * osc; }
;                     }
;                     bf16_t* dst = (pn < 2) ? QA + (size_t)row * 512 + (4 * pn + wc) * 64 : KVA + (size_t)row * 256 + wc * 64;
; #pragma unroll
;                     for (int bj = 0; bj < 2; ++bj)
; #pragma unroll
;                         for (int n = 0; n < 2; ++n) { u32x2 w; w.x = cvt_pk_bf16(v[bj][n][0], v[bj][n][1]); w.y = cvt_pk_bf16(v[bj][n][2], v[bj][n][3]); *(u32x2*)(dst + 32 * bj + 16 * n + 4 * fq) = w; }
	v_pk_mul_f32 v[90:91], v[90:91], v[150:151]
	v_pk_mul_f32 v[92:93], v[92:93], v[152:153]
	v_pk_mul_f32 v[82:83], v[82:83], v[156:157]
	v_pk_mul_f32 v[84:85], v[84:85], v[158:159]
	v_pk_mul_f32 v[94:95], v[94:95], v[160:161]
	v_pk_mul_f32 v[96:97], v[96:97], v[144:145]
	v_pk_mul_f32 v[86:87], v[86:87], v[204:205]
	v_pk_mul_f32 v[88:89], v[88:89], v[140:141]
	v_pk_mul_f32 v[188:189], v[82:83], v[246:247]
	v_pk_mul_f32 v[192:193], v[90:91], v[246:247]
	v_pk_mul_f32 v[190:191], v[84:85], v[248:249]
	v_pk_mul_f32 v[194:195], v[92:93], v[248:249]
	v_pk_fma_f32 v[90:91], v[90:91], v[242:243], v[188:189] neg_lo:[0,0,1] neg_hi:[0,0,1]
	v_pk_fma_f32 v[82:83], v[82:83], v[242:243], v[192:193]
	v_pk_fma_f32 v[92:93], v[92:93], v[244:245], v[190:191] neg_lo:[0,0,1] neg_hi:[0,0,1]
	v_pk_fma_f32 v[84:85], v[84:85], v[244:245], v[194:195]
	v_pk_mul_f32 v[188:189], v[86:87], v[230:231]
	v_pk_mul_f32 v[192:193], v[94:95], v[230:231]
	v_pk_mul_f32 v[190:191], v[88:89], v[232:233]
	v_pk_mul_f32 v[194:195], v[96:97], v[232:233]
	v_pk_fma_f32 v[94:95], v[94:95], v[226:227], v[188:189] neg_lo:[0,0,1] neg_hi:[0,0,1]
	v_pk_fma_f32 v[86:87], v[86:87], v[226:227], v[192:193]
	v_pk_fma_f32 v[96:97], v[96:97], v[228:229], v[190:191] neg_lo:[0,0,1] neg_hi:[0,0,1]
	v_pk_fma_f32 v[88:89], v[88:89], v[228:229], v[194:195]
	v_pk_mul_f32 v[90:91], v[90:91], v[148:149] op_sel_hi:[1,0]
	v_pk_mul_f32 v[92:93], v[92:93], v[148:149] op_sel_hi:[1,0]
	v_pk_mul_f32 v[82:83], v[82:83], v[148:149] op_sel_hi:[1,0]
	v_pk_mul_f32 v[84:85], v[84:85], v[148:149] op_sel_hi:[1,0]
	v_pk_mul_f32 v[94:95], v[94:95], v[148:149] op_sel_hi:[1,0]
	v_pk_mul_f32 v[96:97], v[96:97], v[148:149] op_sel_hi:[1,0]
	v_pk_mul_f32 v[86:87], v[86:87], v[148:149] op_sel_hi:[1,0]
	v_pk_mul_f32 v[88:89], v[88:89], v[148:149] op_sel_hi:[1,0]
	v_cvt_pk_bf16_f32 v90, v90, v91
	v_cvt_pk_bf16_f32 v91, v92, v93
	v_cvt_pk_bf16_f32 v82, v82, v83
	v_cvt_pk_bf16_f32 v83, v84, v85
	v_cvt_pk_bf16_f32 v94, v94, v95
	v_cvt_pk_bf16_f32 v95, v96, v97
	v_cvt_pk_bf16_f32 v86, v86, v87
	v_cvt_pk_bf16_f32 v87, v88, v89
	v_pk_mul_f32 v[26:27], v[26:27], v[150:151]
	v_pk_mul_f32 v[28:29], v[28:29], v[152:153]
	v_pk_mul_f32 v[18:19], v[18:19], v[156:157]
	v_pk_mul_f32 v[20:21], v[20:21], v[158:159]
	v_pk_mul_f32 v[30:31], v[30:31], v[160:161]
	v_pk_mul_f32 v[32:33], v[32:33], v[144:145]
	v_pk_mul_f32 v[22:23], v[22:23], v[204:205]
	v_pk_mul_f32 v[24:25], v[24:25], v[140:141]
	v_pk_mul_f32 v[188:189], v[18:19], v[250:251]
	v_pk_mul_f32 v[192:193], v[26:27], v[250:251]
	v_pk_mul_f32 v[190:191], v[20:21], v[216:217]
	v_pk_mul_f32 v[194:195], v[28:29], v[216:217]
	v_pk_fma_f32 v[26:27], v[26:27], v[212:213], v[188:189] neg_lo:[0,0,1] neg_hi:[0,0,1]
	v_pk_fma_f32 v[18:19], v[18:19], v[212:213], v[192:193]
	v_pk_fma_f32 v[28:29], v[28:29], v[214:215], v[190:191] neg_lo:[0,0,1] neg_hi:[0,0,1]
	v_pk_fma_f32 v[20:21], v[20:21], v[214:215], v[194:195]
	v_pk_mul_f32 v[188:189], v[22:23], v[230:231]
	v_pk_mul_f32 v[192:193], v[30:31], v[230:231]
	v_pk_mul_f32 v[190:191], v[24:25], v[232:233]
	v_pk_mul_f32 v[194:195], v[32:33], v[232:233]
	v_pk_fma_f32 v[30:31], v[30:31], v[226:227], v[188:189] neg_lo:[0,0,1] neg_hi:[0,0,1]
	v_pk_fma_f32 v[22:23], v[22:23], v[226:227], v[192:193]
	v_pk_fma_f32 v[32:33], v[32:33], v[228:229], v[190:191] neg_lo:[0,0,1] neg_hi:[0,0,1]
	v_pk_fma_f32 v[24:25], v[24:25], v[228:229], v[194:195]
	v_pk_mul_f32 v[26:27], v[26:27], v[132:133] op_sel_hi:[1,0]
	v_pk_mul_f32 v[28:29], v[28:29], v[132:133] op_sel_hi:[1,0]
	v_pk_mul_f32 v[18:19], v[18:19], v[132:133] op_sel_hi:[1,0]
	v_pk_mul_f32 v[20:21], v[20:21], v[132:133] op_sel_hi:[1,0]
	v_pk_mul_f32 v[30:31], v[30:31], v[132:133] op_sel_hi:[1,0]
	v_pk_mul_f32 v[32:33], v[32:33], v[132:133] op_sel_hi:[1,0]
	v_pk_mul_f32 v[22:23], v[22:23], v[132:133] op_sel_hi:[1,0]
	v_pk_mul_f32 v[24:25], v[24:25], v[132:133] op_sel_hi:[1,0]
	v_cvt_pk_bf16_f32 v26, v26, v27
	v_cvt_pk_bf16_f32 v27, v28, v29
	v_cvt_pk_bf16_f32 v18, v18, v19
	v_cvt_pk_bf16_f32 v19, v20, v21
	v_cvt_pk_bf16_f32 v30, v30, v31
	v_cvt_pk_bf16_f32 v31, v32, v33
	v_cvt_pk_bf16_f32 v22, v22, v23
	v_cvt_pk_bf16_f32 v23, v24, v25
	s_waitcnt vmcnt(0)
	v_pk_mul_f32 v[74:75], v[74:75], v[150:151]
	v_pk_mul_f32 v[76:77], v[76:77], v[152:153]
	v_pk_mul_f32 v[66:67], v[66:67], v[156:157]
	v_pk_mul_f32 v[68:69], v[68:69], v[158:159]
	v_pk_mul_f32 v[78:79], v[78:79], v[160:161]
	v_pk_mul_f32 v[80:81], v[80:81], v[144:145]
	v_pk_mul_f32 v[70:71], v[70:71], v[204:205]
	v_pk_mul_f32 v[72:73], v[72:73], v[140:141]
	v_pk_mul_f32 v[188:189], v[66:67], v[246:247]
	v_pk_mul_f32 v[192:193], v[74:75], v[246:247]
	v_pk_mul_f32 v[190:191], v[68:69], v[248:249]
	v_pk_mul_f32 v[194:195], v[76:77], v[248:249]
	v_pk_fma_f32 v[74:75], v[74:75], v[242:243], v[188:189] neg_lo:[0,0,1] neg_hi:[0,0,1]
	v_pk_fma_f32 v[66:67], v[66:67], v[242:243], v[192:193]
	v_pk_fma_f32 v[76:77], v[76:77], v[244:245], v[190:191] neg_lo:[0,0,1] neg_hi:[0,0,1]
	v_pk_fma_f32 v[68:69], v[68:69], v[244:245], v[194:195]
	v_pk_mul_f32 v[188:189], v[70:71], v[238:239]
	v_pk_mul_f32 v[192:193], v[78:79], v[238:239]
	v_pk_mul_f32 v[190:191], v[72:73], v[240:241]
	v_pk_mul_f32 v[194:195], v[80:81], v[240:241]
	v_pk_fma_f32 v[78:79], v[78:79], v[234:235], v[188:189] neg_lo:[0,0,1] neg_hi:[0,0,1]
	v_pk_fma_f32 v[70:71], v[70:71], v[234:235], v[192:193]
	v_pk_fma_f32 v[80:81], v[80:81], v[236:237], v[190:191] neg_lo:[0,0,1] neg_hi:[0,0,1]
	v_pk_fma_f32 v[72:73], v[72:73], v[236:237], v[194:195]
	v_pk_mul_f32 v[74:75], v[74:75], v[146:147] op_sel_hi:[1,0]
	v_pk_mul_f32 v[76:77], v[76:77], v[146:147] op_sel_hi:[1,0]
	v_pk_mul_f32 v[66:67], v[66:67], v[146:147] op_sel_hi:[1,0]
; __device__ __forceinline__ unsigned cvt_pk_bf16(float lo, float hi) { unsigned r; asm volatile("v_cvt_pk_bf16_f32 %0, %1, %2" : "=v"(r) : "v"(lo), "v"(hi)); return r; }
;     __device__ __forceinline__ void operator()(const f32x4 (&acc)[2][2][4][2], const Unit& u, int wr, int wc, int fr_, int fq_) const {
;     ...
;                     for (int bj = 0; bj < 2; ++bj)
; #pragma unroll
;                         for (int n = 0; n < 2; ++n) v[bj][n] = acc[ai][bj][m][n] * rstd;
;                     if (!isV) {
;     ...
; #pragma unroll
;                         for (int bj = 0; bj < 2; ++bj)
; #pragma unroll
;                             for (int n = 0; n < 2; ++n) { const f32x4 w = *(const f32x4*)(nw + 32 * bj + 16 * n + 4 * fq); v[bj][n] = v[bj][n] * w * rn; }
;                         const int t = row & (S - 1), gr = t >> 6, gc = t & 63;
;                         const f32x4 c0 = *(const f32x4*)(ropeC + gr * 16 + 4 * fq), s0 = *(const f32x4*)(ropeS + gr * 16 + 4 * fq);
;                         const f32x4 c1 = *(const f32x4*)(ropeC + gc * 16 + 4 * fq), s1 = *(const f32x4*)(ropeS + gc * 16 + 4 * fq);
;                         { const f32x4 x1 = v[0][0], x2 = v[0][1]; v[0][0] = (x1 * c0 - x2 * s0) * osc; v[0][1] = (x2 * c0 + x1 * s0) * osc; }
;                         { const f32x4 x1 = v[1][0], x2 = v[1][1]; v[1][0] = (x1 * c1 - x2 * s1) * osc; v[1][1] = (x2 * c1 + x1 * s1) * osc; }
;                     }
;                     bf16_t* dst = (pn < 2) ? QA + (size_t)row * 512 + (4 * pn + wc) * 64 : KVA + (size_t)row * 256 + wc * 64;
; #pragma unroll
;                     for (int bj = 0; bj < 2; ++bj)
; #pragma unroll
;                         for (int n = 0; n < 2; ++n) { u32x2 w; w.x = cvt_pk_bf16(v[bj][n][0], v[bj][n][1]); w.y = cvt_pk_bf16(v[bj][n][2], v[bj][n][3]); *(u32x2*)(dst + 32 * bj + 16 * n + 4 * fq) = w; }
	v_pk_mul_f32 v[68:69], v[68:69], v[146:147] op_sel_hi:[1,0]
	v_pk_mul_f32 v[78:79], v[78:79], v[146:147] op_sel_hi:[1,0]
	v_pk_mul_f32 v[80:81], v[80:81], v[146:147] op_sel_hi:[1,0]
	v_pk_mul_f32 v[70:71], v[70:71], v[146:147] op_sel_hi:[1,0]
	v_pk_mul_f32 v[72:73], v[72:73], v[146:147] op_sel_hi:[1,0]
	v_cvt_pk_bf16_f32 v74, v74, v75
	v_cvt_pk_bf16_f32 v75, v76, v77
	v_cvt_pk_bf16_f32 v66, v66, v67
	v_cvt_pk_bf16_f32 v67, v68, v69
	v_cvt_pk_bf16_f32 v78, v78, v79
	v_cvt_pk_bf16_f32 v79, v80, v81
	v_cvt_pk_bf16_f32 v70, v70, v71
	v_cvt_pk_bf16_f32 v71, v72, v73
	v_pk_mul_f32 v[10:11], v[10:11], v[150:151]
	v_pk_mul_f32 v[12:13], v[12:13], v[152:153]
	v_pk_mul_f32 v[2:3], v[2:3], v[156:157]
	v_pk_mul_f32 v[4:5], v[4:5], v[158:159]
	v_pk_mul_f32 v[14:15], v[14:15], v[160:161]
	v_pk_mul_f32 v[16:17], v[16:17], v[144:145]
	v_pk_mul_f32 v[6:7], v[6:7], v[204:205]
	v_pk_mul_f32 v[8:9], v[8:9], v[140:141]
	v_pk_mul_f32 v[188:189], v[2:3], v[250:251]
	v_pk_mul_f32 v[192:193], v[10:11], v[250:251]
	v_pk_mul_f32 v[190:191], v[4:5], v[216:217]
	v_pk_mul_f32 v[194:195], v[12:13], v[216:217]
	v_pk_fma_f32 v[10:11], v[10:11], v[212:213], v[188:189] neg_lo:[0,0,1] neg_hi:[0,0,1]
	v_pk_fma_f32 v[2:3], v[2:3], v[212:213], v[192:193]
	v_pk_fma_f32 v[12:13], v[12:13], v[214:215], v[190:191] neg_lo:[0,0,1] neg_hi:[0,0,1]
	v_pk_fma_f32 v[4:5], v[4:5], v[214:215], v[194:195]
	v_pk_mul_f32 v[188:189], v[6:7], v[238:239]
	v_pk_mul_f32 v[192:193], v[14:15], v[238:239]
	v_pk_mul_f32 v[190:191], v[8:9], v[240:241]
	v_pk_mul_f32 v[194:195], v[16:17], v[240:241]
	v_pk_fma_f32 v[14:15], v[14:15], v[234:235], v[188:189] neg_lo:[0,0,1] neg_hi:[0,0,1]
	v_pk_fma_f32 v[6:7], v[6:7], v[234:235], v[192:193]
	v_pk_fma_f32 v[16:17], v[16:17], v[236:237], v[190:191] neg_lo:[0,0,1] neg_hi:[0,0,1]
	v_pk_fma_f32 v[8:9], v[8:9], v[236:237], v[194:195]
	v_pk_mul_f32 v[10:11], v[10:11], v[130:131] op_sel_hi:[1,0]
	v_pk_mul_f32 v[12:13], v[12:13], v[130:131] op_sel_hi:[1,0]
	v_pk_mul_f32 v[2:3], v[2:3], v[130:131] op_sel_hi:[1,0]
	v_pk_mul_f32 v[4:5], v[4:5], v[130:131] op_sel_hi:[1,0]
	v_pk_mul_f32 v[14:15], v[14:15], v[130:131] op_sel_hi:[1,0]
	v_pk_mul_f32 v[16:17], v[16:17], v[130:131] op_sel_hi:[1,0]
	v_pk_mul_f32 v[6:7], v[6:7], v[130:131] op_sel_hi:[1,0]
	v_pk_mul_f32 v[8:9], v[8:9], v[130:131] op_sel_hi:[1,0]
	v_cvt_pk_bf16_f32 v10, v10, v11
	v_cvt_pk_bf16_f32 v11, v12, v13
	v_cvt_pk_bf16_f32 v2, v2, v3
	v_cvt_pk_bf16_f32 v3, v4, v5
	v_cvt_pk_bf16_f32 v14, v14, v15
	v_cvt_pk_bf16_f32 v15, v16, v17
	v_cvt_pk_bf16_f32 v6, v6, v7
	v_cvt_pk_bf16_f32 v7, v8, v9
	s_branch .Lqk_store
.Lqk_v:
	v_pk_mul_f32 v[118:119], v[118:119], v[0:1] op_sel_hi:[1,0]
	v_pk_mul_f32 v[120:121], v[120:121], v[0:1] op_sel_hi:[1,0]
	v_pk_mul_f32 v[114:115], v[114:115], v[0:1] op_sel_hi:[1,0]
	v_pk_mul_f32 v[116:117], v[116:117], v[0:1] op_sel_hi:[1,0]
	v_pk_mul_f32 v[126:127], v[126:127], v[0:1] op_sel_hi:[1,0]
	v_pk_mul_f32 v[128:129], v[128:129], v[0:1] op_sel_hi:[1,0]
	v_pk_mul_f32 v[122:123], v[122:123], v[0:1] op_sel_hi:[1,0]
	v_pk_mul_f32 v[124:125], v[124:125], v[0:1] op_sel_hi:[1,0]
	v_cvt_pk_bf16_f32 v118, v118, v119
	v_cvt_pk_bf16_f32 v119, v120, v121
	v_cvt_pk_bf16_f32 v114, v114, v115
	v_cvt_pk_bf16_f32 v115, v116, v117
	v_cvt_pk_bf16_f32 v126, v126, v127
	v_cvt_pk_bf16_f32 v127, v128, v129
	v_cvt_pk_bf16_f32 v122, v122, v123
	v_cvt_pk_bf16_f32 v123, v124, v125
	v_pk_mul_f32 v[106:107], v[106:107], v[154:155] op_sel_hi:[1,0]
	v_pk_mul_f32 v[108:109], v[108:109], v[154:155] op_sel_hi:[1,0]
	v_pk_mul_f32 v[98:99], v[98:99], v[154:155] op_sel_hi:[1,0]
	v_pk_mul_f32 v[100:101], v[100:101], v[154:155] op_sel_hi:[1,0]
	v_pk_mul_f32 v[110:111], v[110:111], v[154:155] op_sel_hi:[1,0]
	v_pk_mul_f32 v[112:113], v[112:113], v[154:155] op_sel_hi:[1,0]
	v_pk_mul_f32 v[102:103], v[102:103], v[154:155] op_sel_hi:[1,0]
	v_pk_mul_f32 v[104:105], v[104:105], v[154:155] op_sel_hi:[1,0]
	v_cvt_pk_bf16_f32 v106, v106, v107
	v_cvt_pk_bf16_f32 v107, v108, v109
	v_cvt_pk_bf16_f32 v98, v98, v99
	v_cvt_pk_bf16_f32 v99, v100, v101
	v_cvt_pk_bf16_f32 v110, v110, v111
	v_cvt_pk_bf16_f32 v111, v112, v113
	v_cvt_pk_bf16_f32 v102, v102, v103
	v_cvt_pk_bf16_f32 v103, v104, v105
	v_pk_mul_f32 v[90:91], v[90:91], v[148:149] op_sel_hi:[1,0]
	v_pk_mul_f32 v[92:93], v[92:93], v[148:149] op_sel_hi:[1,0]
	v_pk_mul_f32 v[82:83], v[82:83], v[148:149] op_sel_hi:[1,0]
	v_pk_mul_f32 v[84:85], v[84:85], v[148:149] op_sel_hi:[1,0]
	v_pk_mul_f32 v[94:95], v[94:95], v[148:149] op_sel_hi:[1,0]
	v_pk_mul_f32 v[96:97], v[96:97], v[148:149] op_sel_hi:[1,0]
	v_pk_mul_f32 v[86:87], v[86:87], v[148:149] op_sel_hi:[1,0]
	v_pk_mul_f32 v[88:89], v[88:89], v[148:149] op_sel_hi:[1,0]
	v_cvt_pk_bf16_f32 v90, v90, v91
	v_cvt_pk_bf16_f32 v91, v92, v93
	v_cvt_pk_bf16_f32 v82, v82, v83
	v_cvt_pk_bf16_f32 v83, v84, v85
	v_cvt_pk_bf16_f32 v94, v94, v95
	v_cvt_pk_bf16_f32 v95, v96, v97
	v_cvt_pk_bf16_f32 v86, v86, v87
	v_cvt_pk_bf16_f32 v87, v88, v89
	v_pk_mul_f32 v[74:75], v[74:75], v[146:147] op_sel_hi:[1,0]
	v_pk_mul_f32 v[76:77], v[76:77], v[146:147] op_sel_hi:[1,0]
	v_pk_mul_f32 v[66:67], v[66:67], v[146:147] op_sel_hi:[1,0]
	v_pk_mul_f32 v[68:69], v[68:69], v[146:147] op_sel_hi:[1,0]
	v_pk_mul_f32 v[78:79], v[78:79], v[146:147] op_sel_hi:[1,0]
	v_pk_mul_f32 v[80:81], v[80:81], v[146:147] op_sel_hi:[1,0]
	v_pk_mul_f32 v[70:71], v[70:71], v[146:147] op_sel_hi:[1,0]
; __device__ __forceinline__ unsigned cvt_pk_bf16(float lo, float hi) { unsigned r; asm volatile("v_cvt_pk_bf16_f32 %0, %1, %2" : "=v"(r) : "v"(lo), "v"(hi)); return r; }
;     __device__ __forceinline__ void operator()(const f32x4 (&acc)[2][2][4][2], const Unit& u, int wr, int wc, int fr_, int fq_) const {
;     ...
;                     for (int bj = 0; bj < 2; ++bj)
; #pragma unroll
;                         for (int n = 0; n < 2; ++n) v[bj][n] = acc[ai][bj][m][n] * rstd;
;                     if (!isV) {
;                         float s = 0.f;
; #pragma unroll
;                         for (int bj = 0; bj < 2; ++bj)
; #pragma unroll
;                             for (int n = 0; n < 2; ++n) { const f32x4 x = v[bj][n]; s += (x[0] * x[0] + x[1] * x[1]) + (x[2] * x[2] + x[3] * x[3]); }
;                         s += __shfl_xor(s, 16); s += __shfl_xor(s, 32);
;                         const float rn = rsqrtf(s * (1.0f / 64.0f) + 1e-6f);
; #pragma unroll
;                         for (int bj = 0; bj < 2; ++bj)
; #pragma unroll
;                             for (int n = 0; n < 2; ++n) { const f32x4 w = *(const f32x4*)(nw + 32 * bj + 16 * n + 4 * fq); v[bj][n] = v[bj][n] * w * rn; }
;                         const int t = row & (S - 1), gr = t >> 6, gc = t & 63;
;                         const f32x4 c0 = *(const f32x4*)(ropeC + gr * 16 + 4 * fq), s0 = *(const f32x4*)(ropeS + gr * 16 + 4 * fq);
;                         const f32x4 c1 = *(const f32x4*)(ropeC + gc * 16 + 4 * fq), s1 = *(const f32x4*)(ropeS + gc * 16 + 4 * fq);
;                         { const f32x4 x1 = v[0][0], x2 = v[0][1]; v[0][0] = (x1 * c0 - x2 * s0) * osc; v[0][1] = (x2 * c0 + x1 * s0) * osc; }
;                         { const f32x4 x1 = v[1][0], x2 = v[1][1]; v[1][0] = (x1 * c1 - x2 * s1) * osc; v[1][1] = (x2 * c1 + x1 * s1) * osc; }
;                     }
;                     bf16_t* dst = (pn < 2) ? QA + (size_t)row * 512 + (4 * pn + wc) * 64 : KVA + (size_t)row * 256 + wc * 64;
; #pragma unroll
;                     for (int bj = 0; bj < 2; ++bj)
; #pragma unroll
;                         for (int n = 0; n < 2; ++n) { u32x2 w; w.x = cvt_pk_bf16(v[bj][n][0], v[bj][n][1]); w.y = cvt_pk_bf16(v[bj][n][2], v[bj][n][3]); *(u32x2*)(dst + 32 * bj + 16 * n + 4 * fq) = w; }
	v_pk_mul_f32 v[72:73], v[72:73], v[146:147] op_sel_hi:[1,0]
	v_cvt_pk_bf16_f32 v74, v74, v75
	v_cvt_pk_bf16_f32 v75, v76, v77
	v_cvt_pk_bf16_f32 v66, v66, v67
	v_cvt_pk_bf16_f32 v67, v68, v69
	v_cvt_pk_bf16_f32 v78, v78, v79
	v_cvt_pk_bf16_f32 v79, v80, v81
	v_cvt_pk_bf16_f32 v70, v70, v71
	v_cvt_pk_bf16_f32 v71, v72, v73
	v_pk_mul_f32 v[58:59], v[58:59], v[142:143] op_sel_hi:[1,0]
	v_pk_mul_f32 v[60:61], v[60:61], v[142:143] op_sel_hi:[1,0]
	v_pk_mul_f32 v[50:51], v[50:51], v[142:143] op_sel_hi:[1,0]
	v_pk_mul_f32 v[52:53], v[52:53], v[142:143] op_sel_hi:[1,0]
	v_pk_mul_f32 v[62:63], v[62:63], v[142:143] op_sel_hi:[1,0]
	v_pk_mul_f32 v[64:65], v[64:65], v[142:143] op_sel_hi:[1,0]
	v_pk_mul_f32 v[54:55], v[54:55], v[142:143] op_sel_hi:[1,0]
	v_pk_mul_f32 v[56:57], v[56:57], v[142:143] op_sel_hi:[1,0]
	v_cvt_pk_bf16_f32 v58, v58, v59
	v_cvt_pk_bf16_f32 v59, v60, v61
	v_cvt_pk_bf16_f32 v50, v50, v51
	v_cvt_pk_bf16_f32 v51, v52, v53
	v_cvt_pk_bf16_f32 v62, v62, v63
	v_cvt_pk_bf16_f32 v63, v64, v65
	v_cvt_pk_bf16_f32 v54, v54, v55
	v_cvt_pk_bf16_f32 v55, v56, v57
	v_pk_mul_f32 v[42:43], v[42:43], v[138:139] op_sel_hi:[1,0]
	v_pk_mul_f32 v[44:45], v[44:45], v[138:139] op_sel_hi:[1,0]
	v_pk_mul_f32 v[34:35], v[34:35], v[138:139] op_sel_hi:[1,0]
	v_pk_mul_f32 v[36:37], v[36:37], v[138:139] op_sel_hi:[1,0]
	v_pk_mul_f32 v[46:47], v[46:47], v[138:139] op_sel_hi:[1,0]
	v_pk_mul_f32 v[48:49], v[48:49], v[138:139] op_sel_hi:[1,0]
	v_pk_mul_f32 v[38:39], v[38:39], v[138:139] op_sel_hi:[1,0]
	v_pk_mul_f32 v[40:41], v[40:41], v[138:139] op_sel_hi:[1,0]
	v_cvt_pk_bf16_f32 v42, v42, v43
	v_cvt_pk_bf16_f32 v43, v44, v45
	v_cvt_pk_bf16_f32 v34, v34, v35
	v_cvt_pk_bf16_f32 v35, v36, v37
	v_cvt_pk_bf16_f32 v46, v46, v47
	v_cvt_pk_bf16_f32 v47, v48, v49
	v_cvt_pk_bf16_f32 v38, v38, v39
	v_cvt_pk_bf16_f32 v39, v40, v41
	v_pk_mul_f32 v[26:27], v[26:27], v[132:133] op_sel_hi:[1,0]
	v_pk_mul_f32 v[28:29], v[28:29], v[132:133] op_sel_hi:[1,0]
	v_pk_mul_f32 v[18:19], v[18:19], v[132:133] op_sel_hi:[1,0]
	v_pk_mul_f32 v[20:21], v[20:21], v[132:133] op_sel_hi:[1,0]
	v_pk_mul_f32 v[30:31], v[30:31], v[132:133] op_sel_hi:[1,0]
	v_pk_mul_f32 v[32:33], v[32:33], v[132:133] op_sel_hi:[1,0]
	v_pk_mul_f32 v[22:23], v[22:23], v[132:133] op_sel_hi:[1,0]
	v_pk_mul_f32 v[24:25], v[24:25], v[132:133] op_sel_hi:[1,0]
	v_cvt_pk_bf16_f32 v26, v26, v27
	v_cvt_pk_bf16_f32 v27, v28, v29
	v_cvt_pk_bf16_f32 v18, v18, v19
	v_cvt_pk_bf16_f32 v19, v20, v21
	v_cvt_pk_bf16_f32 v30, v30, v31
	v_cvt_pk_bf16_f32 v31, v32, v33
	v_cvt_pk_bf16_f32 v22, v22, v23
	v_cvt_pk_bf16_f32 v23, v24, v25
	v_pk_mul_f32 v[10:11], v[10:11], v[130:131] op_sel_hi:[1,0]
	v_pk_mul_f32 v[12:13], v[12:13], v[130:131] op_sel_hi:[1,0]
	v_pk_mul_f32 v[2:3], v[2:3], v[130:131] op_sel_hi:[1,0]
	v_pk_mul_f32 v[4:5], v[4:5], v[130:131] op_sel_hi:[1,0]
	v_pk_mul_f32 v[14:15], v[14:15], v[130:131] op_sel_hi:[1,0]
	v_pk_mul_f32 v[16:17], v[16:17], v[130:131] op_sel_hi:[1,0]
	v_pk_mul_f32 v[6:7], v[6:7], v[130:131] op_sel_hi:[1,0]
	v_pk_mul_f32 v[8:9], v[8:9], v[130:131] op_sel_hi:[1,0]
	v_cvt_pk_bf16_f32 v10, v10, v11
	v_cvt_pk_bf16_f32 v11, v12, v13
	v_cvt_pk_bf16_f32 v2, v2, v3
	v_cvt_pk_bf16_f32 v3, v4, v5
	v_cvt_pk_bf16_f32 v14, v14, v15
	v_cvt_pk_bf16_f32 v15, v16, v17
	v_cvt_pk_bf16_f32 v6, v6, v7
	v_cvt_pk_bf16_f32 v7, v8, v9
.Lqk_store:
	v_lshl_add_u32 v133, v186, s36, v137
	global_store_dwordx2 v133, v[118:119], s[0:1]
	global_store_dwordx2 v133, v[114:115], s[0:1] offset:32
	global_store_dwordx2 v133, v[126:127], s[0:1] offset:64
	global_store_dwordx2 v133, v[122:123], s[0:1] offset:96
	v_lshl_add_u32 v133, v184, s36, v137
	global_store_dwordx2 v133, v[106:107], s[0:1]
	global_store_dwordx2 v133, v[98:99], s[0:1] offset:32
	global_store_dwordx2 v133, v[110:111], s[0:1] offset:64
	global_store_dwordx2 v133, v[102:103], s[0:1] offset:96
	v_lshl_add_u32 v133, v182, s36, v137
	global_store_dwordx2 v133, v[90:91], s[0:1]
	global_store_dwordx2 v133, v[82:83], s[0:1] offset:32
	global_store_dwordx2 v133, v[94:95], s[0:1] offset:64
	global_store_dwordx2 v133, v[86:87], s[0:1] offset:96
	v_lshl_add_u32 v133, v180, s36, v137
	global_store_dwordx2 v133, v[74:75], s[0:1]
	global_store_dwordx2 v133, v[66:67], s[0:1] offset:32
	global_store_dwordx2 v133, v[78:79], s[0:1] offset:64
	global_store_dwordx2 v133, v[70:71], s[0:1] offset:96
	v_lshl_add_u32 v133, v178, s36, v137
	global_store_dwordx2 v133, v[58:59], s[0:1]
	global_store_dwordx2 v133, v[50:51], s[0:1] offset:32
	global_store_dwordx2 v133, v[62:63], s[0:1] offset:64
	global_store_dwordx2 v133, v[54:55], s[0:1] offset:96
	v_lshl_add_u32 v133, v176, s36, v137
	global_store_dwordx2 v133, v[42:43], s[0:1]
	global_store_dwordx2 v133, v[34:35], s[0:1] offset:32
	global_store_dwordx2 v133, v[46:47], s[0:1] offset:64
	global_store_dwordx2 v133, v[38:39], s[0:1] offset:96
	v_lshl_add_u32 v133, v174, s36, v137
	global_store_dwordx2 v133, v[26:27], s[0:1]
	global_store_dwordx2 v133, v[18:19], s[0:1] offset:32
	global_store_dwordx2 v133, v[30:31], s[0:1] offset:64
	global_store_dwordx2 v133, v[22:23], s[0:1] offset:96
	v_lshl_add_u32 v133, v172, s36, v137
	global_store_dwordx2 v133, v[10:11], s[0:1]
	global_store_dwordx2 v133, v[2:3], s[0:1] offset:32
	global_store_dwordx2 v133, v[14:15], s[0:1] offset:64
	global_store_dwordx2 v133, v[6:7], s[0:1] offset:96
	s_andn2_b64 vcc, exec, s[38:39]
	s_mov_b64 s[0:1], -1
	s_cbranch_vccnz .LBB0_403
